# RET chain: LDS-DMA m0 offsets by SALU adds from one readfirstlane (8 fewer VALU-to-SALU hops per step)
# baseline (speedup 1.0000x reference)
; #define LAS __attribute__((address_space(3)))
; DI unsigned pk2(float lo, float hi) { const f32x2 v = {lo, hi}; const hbf16x2 b = __builtin_convertvector(v, hbf16x2); return __builtin_bit_cast(unsigned, b); }
; #define MFMA16(a, b, c) __builtin_amdgcn_mfma_f32_16x16x32_bf16((a), (b), (c), 0, 0, 0)
; DI void ret_chain_phase(const Ctx& a, LAS unsigned char* lds) {
;     ...
;             if (s + 1 < 68) RC_DMA_QK(s + 1);
; #pragma unroll
;             for (int vv = 0; vv < 2; ++vv) {
;                 const int vt = 2 * half + vv;
; #pragma unroll
;                 for (int k2 = 0; k2 < 2; ++k2) {
;                     const bf16x8 vf = *(const LAS bf16x8*)(lds + A128(RC_SVT, vt, k2));
;                     const bf16x8 pf = *(const LAS bf16x8*)(lds + A128(RC_SP, it, k2));
;                     accO[vv] = MFMA16(vf, pf, accO[vv]);
;                 }
;                 u32x2 w; w.x = pk2(accO[vv][0], accO[vv][1]); w.y = pk2(accO[vv][2], accO[vv][3]);
;                 *(u32x2*)(O + (size_t)(row0 + icol) * 2048 + h * 512 + vs * 64 + 16 * vt + 4 * fq) = w;
;             }
;             bf16x8 vfr[4][2];
; #pragma unroll
;             for (int vt = 0; vt < 4; ++vt) { vfr[vt][0] = *(const LAS bf16x8*)(lds + A128(RC_SVT, vt, 0)); vfr[vt][1] = *(const LAS bf16x8*)(lds + A128(RC_SVT, vt, 1)); }
; #pragma unroll
;             for (int di = 0; di < 2; ++di) {
;                 const int dt = 2 * wid + di;
;                 bf16x8 kt[2];
; #pragma unroll
;                 for (int k2 = 0; k2 < 2; ++k2) kt[k2] = *(const LAS bf16x8*)(lds + A128(RC_SKT, dt, k2));
; #pragma unroll
;                 for (int vt = 0; vt < 4; ++vt) {
;                     f32x4 sacc = accS[di][vt] * cdec;
;                     sacc = MFMA16(kt[0], vfr[vt][0], sacc); sacc = MFMA16(kt[1], vfr[vt][1], sacc);
;                     accS[di][vt] = sacc;
.LBB0_211:
	s_lshl_b32 s20, s30, 6
	s_add_i32 s20, s20, s31
	s_ashr_i32 s21, s20, 31
	s_lshl_b64 s[20:21], s[20:21], 11
	v_lshl_add_u64 v[60:61], s[20:21], 0, v[116:117]
	v_readfirstlane_b32 s100, v172
	v_lshl_add_u64 v[62:63], s[76:77], 0, v[60:61]
	s_add_i32 m0, s100, 0x0
	v_lshl_add_u64 v[60:61], s[80:81], 0, v[60:61]
	global_load_lds_dwordx4 v[62:63], off
	s_add_i32 m0, s100, 0x8000
	s_nop 0
	global_load_lds_dwordx4 v[60:61], off
	v_lshl_add_u64 v[64:65], v[62:63], 0, s[52:53]
	s_add_i32 m0, s100, 0x2000
	s_nop 0
	global_load_lds_dwordx4 v[64:65], off
	v_lshl_add_u64 v[64:65], v[60:61], 0, s[52:53]
	s_add_i32 m0, s100, 0xa000
	s_nop 0
	global_load_lds_dwordx4 v[64:65], off
	v_lshl_add_u64 v[64:65], v[62:63], 0, s[28:29]
	s_add_i32 m0, s100, 0x4000
	s_nop 0
	global_load_lds_dwordx4 v[64:65], off
	v_lshl_add_u64 v[64:65], v[60:61], 0, s[28:29]
	s_add_i32 m0, s100, 0xc000
	s_nop 0
	global_load_lds_dwordx4 v[64:65], off
	v_lshl_add_u64 v[62:63], v[62:63], 0, s[68:69]
	s_add_i32 m0, s100, 0x6000
	s_nop 0
	global_load_lds_dwordx4 v[62:63], off
	v_lshl_add_u64 v[60:61], v[60:61], 0, s[68:69]
	s_add_i32 m0, s100, 0xe000
	v_lshrrev_b32_e32 v68, 1, v105
	global_load_lds_dwordx4 v[60:61], off
	v_add_u32_e32 v60, s50, v122
	v_ashrrev_i32_e32 v61, 31, v60
	v_lshlrev_b64 v[60:61], 12, v[60:61]
	v_lshl_add_u64 v[198:199], v[108:109], 0, v[60:61]
	v_lshlrev_b32_e32 v208, 7, v105
	v_bitop3_b32 v60, v68, v121, 7 bitop3:0x6c
	v_lshlrev_b32_e32 v209, 4, v60
	v_bitop3_b32 v60, v68, v129, 7 bitop3:0x6c
	v_lshlrev_b32_e32 v219, 4, v60
	v_pk_mul_f32 v[58:59], v[112:113], v[86:87]
	v_pk_mul_f32 v[56:57], v[110:111], v[84:85]
	v_pk_mul_f32 v[54:55], v[112:113], v[54:55]
	v_pk_mul_f32 v[52:53], v[110:111], v[52:53]
	v_add3_u32 v250, v128, v208, v209
	ds_read_b128 v[64:67], v250
	v_add3_u32 v250, v128, v208, v219
	ds_read_b128 v[68:71], v250
	v_add3_u32 v250, s2, v208, v209
	ds_read_b128 v[60:63], v250
	v_add3_u32 v250, s2, v208, v219
	ds_read_b128 v[72:75], v250
	v_add3_u32 v250, s84, v208, v209
	ds_read_b128 v[76:79], v250
	v_add3_u32 v250, s84, v208, v219
	ds_read_b128 v[80:83], v250
	v_add3_u32 v250, s85, v208, v209
	ds_read_b128 v[230:233], v250
	v_add3_u32 v250, s85, v208, v219
	ds_read_b128 v[234:237], v250
	v_add3_u32 v250, s24, v208, v209
	ds_read_b128 v[238:241], v250
	v_add3_u32 v250, s24, v208, v219
	ds_read_b128 v[242:245], v250
	v_add3_u32 v250, v168, v208, v209
	ds_read_b128 v[246:249], v250
	v_add3_u32 v250, v168, v208, v219
	ds_read_b128 v[194:197], v250
	v_add3_u32 v250, v169, v208, v209
	ds_read_b128 v[222:225], v250
	v_add3_u32 v250, v169, v208, v219
	ds_read_b128 v[84:87], v250
	v_mov_b32_e32 v105, v104
	v_readfirstlane_b32 s20, v200
	v_pk_mul_f32 v[0:1], v[104:105], v[0:1]
	v_pk_mul_f32 v[2:3], v[104:105], v[2:3]
	v_pk_mul_f32 v[4:5], v[104:105], v[4:5]
	v_pk_mul_f32 v[6:7], v[104:105], v[6:7]
	v_pk_mul_f32 v[8:9], v[104:105], v[8:9]
	v_pk_mul_f32 v[10:11], v[104:105], v[10:11]
	v_pk_mul_f32 v[12:13], v[104:105], v[12:13]
	v_pk_mul_f32 v[14:15], v[104:105], v[14:15]
	v_pk_mul_f32 v[16:17], v[104:105], v[16:17]
	v_pk_mul_f32 v[18:19], v[104:105], v[18:19]
	v_pk_mul_f32 v[20:21], v[104:105], v[20:21]
	v_pk_mul_f32 v[22:23], v[104:105], v[22:23]
	v_pk_mul_f32 v[24:25], v[104:105], v[24:25]
	v_pk_mul_f32 v[26:27], v[104:105], v[26:27]
	v_pk_mul_f32 v[28:29], v[104:105], v[28:29]
	v_pk_mul_f32 v[30:31], v[104:105], v[30:31]
	s_cmp_lt_u32 s20, 0x100
	s_cbranch_scc0 .Lrc_h1
	s_waitcnt lgkmcnt(8)
	v_mfma_f32_16x16x32_bf16 v[56:59], v[60:63], v[64:67], v[56:59]
	v_mfma_f32_16x16x32_bf16 v[56:59], v[72:75], v[68:71], v[56:59]
	v_mfma_f32_16x16x32_bf16 v[52:55], v[76:79], v[64:67], v[52:55]
	v_mfma_f32_16x16x32_bf16 v[52:55], v[80:83], v[68:71], v[52:55]
	s_branch .Lrc_hj

; #define LAS __attribute__((address_space(3)))
; __global__ void __launch_bounds__(NTHREADS) mega(Args a) {
;     extern __shared__ __attribute__((aligned(16))) unsigned char lds_raw[];
;     LAS unsigned char* lds = (LAS unsigned char*)lds_raw;
;     ...
;     volatile LAS unsigned* bst = (volatile LAS unsigned*)(lds + LDS_PHASE_BYTES);
;     if (threadIdx.x < 2) bst[threadIdx.x] = 0u;
;     __syncthreads();
;     const XcdBarrier xbar = xcd_barrier_post((unsigned*)(a.ws + OFF_BAR), bst);
;     ...
;     for (int ph = a.ph_lo; ph < a.ph_hi; ++ph) {
	.amdhsa_kernel _Z4mega4Args
		.amdhsa_group_segment_fixed_size 0
		.amdhsa_private_segment_fixed_size 0
		.amdhsa_kernarg_size 464
		.amdhsa_user_sgpr_count 2
		.amdhsa_user_sgpr_dispatch_ptr 0
		.amdhsa_user_sgpr_queue_ptr 0
		.amdhsa_user_sgpr_kernarg_segment_ptr 1
		.amdhsa_user_sgpr_dispatch_id 0
		.amdhsa_user_sgpr_kernarg_preload_length 0
		.amdhsa_user_sgpr_kernarg_preload_offset 0
		.amdhsa_user_sgpr_private_segment_size 0
		.amdhsa_uses_dynamic_stack 0
		.amdhsa_enable_private_segment 0
		.amdhsa_system_sgpr_workgroup_id_x 1
		.amdhsa_system_sgpr_workgroup_id_y 0
		.amdhsa_system_sgpr_workgroup_id_z 0
		.amdhsa_system_sgpr_workgroup_info 0
		.amdhsa_system_vgpr_workitem_id 2
		.amdhsa_next_free_vgpr 256
		.amdhsa_next_free_sgpr 101
		.amdhsa_accum_offset 256
		.amdhsa_reserve_vcc 1
		.amdhsa_float_round_mode_32 0
		.amdhsa_float_round_mode_16_64 0
		.amdhsa_float_denorm_mode_32 3
		.amdhsa_float_denorm_mode_16_64 3
		.amdhsa_dx10_clamp 1
		.amdhsa_ieee_mode 1
		.amdhsa_fp16_overflow 0
		.amdhsa_tg_split 0
		.amdhsa_exception_fp_ieee_invalid_op 0
		.amdhsa_exception_fp_denorm_src 0
		.amdhsa_exception_fp_ieee_div_zero 0
		.amdhsa_exception_fp_ieee_overflow 0
		.amdhsa_exception_fp_ieee_underflow 0
		.amdhsa_exception_fp_ieee_inexact 0
		.amdhsa_exception_int_div_zero 0
	.end_amdhsa_kernel

; #define LAS __attribute__((address_space(3)))
; __global__ void __launch_bounds__(NTHREADS) mega(Args a) {
;     extern __shared__ __attribute__((aligned(16))) unsigned char lds_raw[];
;     LAS unsigned char* lds = (LAS unsigned char*)lds_raw;
;     ...
;     volatile LAS unsigned* bst = (volatile LAS unsigned*)(lds + LDS_PHASE_BYTES);
;     if (threadIdx.x < 2) bst[threadIdx.x] = 0u;
;     __syncthreads();
;     const XcdBarrier xbar = xcd_barrier_post((unsigned*)(a.ws + OFF_BAR), bst);
;     ...
;     for (int ph = a.ph_lo; ph < a.ph_hi; ++ph) {
amdhsa.kernels:
  - .agpr_count:     0
    .args:
      - .offset:         0
        .size:           208
        .value_kind:     by_value
      - .offset:         208
        .size:           4
        .value_kind:     hidden_block_count_x
      - .offset:         212
        .size:           4
        .value_kind:     hidden_block_count_y
      - .offset:         216
        .size:           4
        .value_kind:     hidden_block_count_z
      - .offset:         220
        .size:           2
        .value_kind:     hidden_group_size_x
      - .offset:         222
        .size:           2
        .value_kind:     hidden_group_size_y
      - .offset:         224
        .size:           2
        .value_kind:     hidden_group_size_z
      - .offset:         226
        .size:           2
        .value_kind:     hidden_remainder_x
      - .offset:         228
        .size:           2
        .value_kind:     hidden_remainder_y
      - .offset:         230
        .size:           2
        .value_kind:     hidden_remainder_z
      - .offset:         248
        .size:           8
        .value_kind:     hidden_global_offset_x
      - .offset:         256
        .size:           8
        .value_kind:     hidden_global_offset_y
      - .offset:         264
        .size:           8
        .value_kind:     hidden_global_offset_z
      - .offset:         272
        .size:           2
        .value_kind:     hidden_grid_dims
      - .offset:         296
        .size:           8
        .value_kind:     hidden_multigrid_sync_arg
      - .offset:         328
        .size:           4
        .value_kind:     hidden_dynamic_lds_size
    .group_segment_fixed_size: 0
    .kernarg_segment_align: 8
    .kernarg_segment_size: 464
    .language:       OpenCL C
    .language_version:
      - 2
      - 0
    .max_flat_workgroup_size: 512
    .name:           _Z4mega4Args
    .private_segment_fixed_size: 0
    .sgpr_count:     107
    .sgpr_spill_count: 258
    .symbol:         _Z4mega4Args.kd
    .uniform_work_group_size: 1
    .uses_dynamic_stack: false
    .vgpr_count:     256
    .vgpr_spill_count: 0
    .wavefront_size: 64
